# v49_cmp2
# speedup vs baseline: 1.0106x; 1.0065x over previous
; #define LAS __attribute__((address_space(3)))
; DI void compress_item(const Ctx& c, const Args& a, int L, int it, LAS unsigned char* lds, int wave, int lane, int tid) {
;     ...
;     {
;         LAS float* bl = (LAS float*)(lds + 69632);
;         if (tid < 256) { const float* pb = (const float*)(a.ws + WS_PB) + kv * 4096 + tid; float s = 0.f;
; #pragma unroll
;             for (int ch = 0; ch < 16; ++ch) s += pb[ch * 256];
;             bl[tid] = s; } }
.LBB0_1126:
	s_andn2_b64 vcc, exec, s[8:9]
	s_cbranch_vccnz .LBB0_1151
	s_and_b64 vcc, exec, s[6:7]
	s_cbranch_vccnz .LBB0_1151
	s_ashr_i32 s8, s36, 3
	s_movk_i32 s6, 0x100
	s_and_b32 s10, s8, 1
	v_cmp_gt_i32_e32 vcc, s6, v34
	s_and_saveexec_b64 s[6:7], vcc
	s_cbranch_execz .LBB0_1130
	s_lshl_b32 s9, s10, 14
	s_add_u32 s12, s38, s9
	s_addc_u32 s13, s39, 0
	v_ashrrev_i32_e32 v35, 31, v34
	v_lshl_add_u64 v[2:3], v[34:35], 2, s[12:13]
	s_mov_b64 s[12:13], 0x22210000
	v_lshl_add_u64 v[4:5], v[2:3], 0, s[12:13]
	s_mov_b64 s[12:13], 0x22211000
	v_lshl_add_u64 v[6:7], v[2:3], 0, s[12:13]
	s_mov_b64 s[12:13], 0x22212000
	v_lshl_add_u64 v[8:9], v[2:3], 0, s[12:13]
	s_mov_b64 s[12:13], 0x22213000
	v_lshl_add_u64 v[10:11], v[2:3], 0, s[12:13]
	global_load_dword v198, v[4:5], off
	global_load_dword v199, v[4:5], off offset:1024
	global_load_dword v200, v[4:5], off offset:2048
	global_load_dword v201, v[4:5], off offset:3072
	global_load_dword v202, v[6:7], off
	global_load_dword v203, v[6:7], off offset:1024
	global_load_dword v204, v[6:7], off offset:2048
	global_load_dword v205, v[6:7], off offset:3072
	global_load_dword v206, v[8:9], off
	global_load_dword v207, v[8:9], off offset:1024
	global_load_dword v208, v[8:9], off offset:2048
	global_load_dword v209, v[8:9], off offset:3072
	global_load_dword v210, v[10:11], off
	global_load_dword v211, v[10:11], off offset:1024
	global_load_dword v212, v[10:11], off offset:2048
	global_load_dword v213, v[10:11], off offset:3072
	s_waitcnt vmcnt(0)
	v_add_f32_e32 v0, 0, v198
	v_add_f32_e32 v0, v0, v199
	v_add_f32_e32 v0, v0, v200
	v_add_f32_e32 v0, v0, v201
	v_add_f32_e32 v0, v0, v202
	v_add_f32_e32 v0, v0, v203
	v_add_f32_e32 v0, v0, v204
	v_add_f32_e32 v0, v0, v205
	v_add_f32_e32 v0, v0, v206
	v_add_f32_e32 v0, v0, v207
	v_add_f32_e32 v0, v0, v208
	v_add_f32_e32 v0, v0, v209
	v_add_f32_e32 v0, v0, v210
	v_add_f32_e32 v0, v0, v211
	v_add_f32_e32 v0, v0, v212
	v_add_f32_e32 v0, v0, v213
	v_lshl_add_u32 v2, v34, 2, 0
	v_add_u32_e32 v2, 0x11000, v2
	ds_write_b32 v2, v0

; #define LAS __attribute__((address_space(3)))
; DI void compress_item(const Ctx& c, const Args& a, int L, int it, LAS unsigned char* lds, int wave, int lane, int tid) {
;     ...
;     {
;         const int tok0 = 512 * ct;
;         for (int idx = tid; idx < 528 * 8; idx += 512) { const int row = idx >> 3, ch = idx & 7; int tok = tok0 + row; tok = tok < SEQ ? tok : SEQ - 1;
;             const v4u v = *(const v4u*)(c.P + (size_t)tok * PP + colP + 8 * ch); *(LAS v4u*)(lds + row * 128 + ((ch ^ ((row >> 4) & 7)) << 4)) = v; }
;         __syncthreads(); }
.LBB0_1132:
	v_ashrrev_i32_e32 v8, 3, v3
	v_and_b32_e32 v0, 56, v2
	v_lshlrev_b32_e32 v0, 1, v0
	v_add_u32_e32 v9, s7, v8
	v_mov_b32_e32 v10, v9
	v_min_i32_e32 v10, 0x3fff, v10
	v_mov_b64_e32 v[4:5], s[14:15]
	v_mad_i64_i32 v[4:5], s[42:43], v10, s56, v[4:5]
	v_lshl_add_u64 v[4:5], v[4:5], 0, v[0:1]
	global_load_dwordx4 v[198:201], v[4:5], off
	v_add_u32_e32 v10, 0x40, v9
	v_min_i32_e32 v10, 0x3fff, v10
	v_mov_b64_e32 v[4:5], s[14:15]
	v_mad_i64_i32 v[4:5], s[42:43], v10, s56, v[4:5]
	v_lshl_add_u64 v[4:5], v[4:5], 0, v[0:1]
	global_load_dwordx4 v[202:205], v[4:5], off
	v_add_u32_e32 v10, 0x80, v9
	v_min_i32_e32 v10, 0x3fff, v10
	v_mov_b64_e32 v[4:5], s[14:15]
	v_mad_i64_i32 v[4:5], s[42:43], v10, s56, v[4:5]
	v_lshl_add_u64 v[4:5], v[4:5], 0, v[0:1]
	global_load_dwordx4 v[206:209], v[4:5], off
	v_add_u32_e32 v10, 0xc0, v9
	v_min_i32_e32 v10, 0x3fff, v10
	v_mov_b64_e32 v[4:5], s[14:15]
	v_mad_i64_i32 v[4:5], s[42:43], v10, s56, v[4:5]
	v_lshl_add_u64 v[4:5], v[4:5], 0, v[0:1]
	global_load_dwordx4 v[210:213], v[4:5], off
	v_add_u32_e32 v10, 0x100, v9
	v_min_i32_e32 v10, 0x3fff, v10
	v_mov_b64_e32 v[4:5], s[14:15]
	v_mad_i64_i32 v[4:5], s[42:43], v10, s56, v[4:5]
	v_lshl_add_u64 v[4:5], v[4:5], 0, v[0:1]
	global_load_dwordx4 v[214:217], v[4:5], off
	v_add_u32_e32 v10, 0x140, v9
	v_min_i32_e32 v10, 0x3fff, v10
	v_mov_b64_e32 v[4:5], s[14:15]
	v_mad_i64_i32 v[4:5], s[42:43], v10, s56, v[4:5]
	v_lshl_add_u64 v[4:5], v[4:5], 0, v[0:1]
	global_load_dwordx4 v[218:221], v[4:5], off
	v_add_u32_e32 v10, 0x180, v9
	v_min_i32_e32 v10, 0x3fff, v10
	v_mov_b64_e32 v[4:5], s[14:15]
	v_mad_i64_i32 v[4:5], s[42:43], v10, s56, v[4:5]
	v_lshl_add_u64 v[4:5], v[4:5], 0, v[0:1]
	global_load_dwordx4 v[222:225], v[4:5], off
	v_add_u32_e32 v10, 0x1c0, v9
	v_min_i32_e32 v10, 0x3fff, v10
	v_mov_b64_e32 v[4:5], s[14:15]
	v_mad_i64_i32 v[4:5], s[42:43], v10, s56, v[4:5]
	v_lshl_add_u64 v[4:5], v[4:5], 0, v[0:1]
	global_load_dwordx4 v[226:229], v[4:5], off
	v_cmp_gt_u32_e32 vcc, 0x80, v3
	s_and_saveexec_b64 s[16:17], vcc
	s_cbranch_execz .Lcmp2_ld8
	v_add_u32_e32 v10, 0x200, v9
	v_min_i32_e32 v10, 0x3fff, v10
	v_mov_b64_e32 v[4:5], s[14:15]
	v_mad_i64_i32 v[4:5], s[42:43], v10, s56, v[4:5]
	v_lshl_add_u64 v[4:5], v[4:5], 0, v[0:1]
	global_load_dwordx4 v[240:243], v[4:5], off
.Lcmp2_ld8:
	s_or_b64 exec, exec, s[16:17]
	v_lshlrev_b32_e32 v11, 7, v8
	v_lshrrev_b32_e32 v12, 7, v3
	v_xor_b32_e32 v12, v12, v3
	v_lshlrev_b32_e32 v12, 4, v12
	v_and_b32_e32 v12, 0x70, v12
	v_add3_u32 v11, 0, v11, v12
	v_xor_b32_e32 v12, 64, v11
	s_waitcnt vmcnt(0)
	ds_write_b128 v11, v[198:201]
	ds_write_b128 v12, v[202:205] offset:8192
	ds_write_b128 v11, v[206:209] offset:16384
	ds_write_b128 v12, v[210:213] offset:24576
	ds_write_b128 v11, v[214:217] offset:32768
	ds_write_b128 v12, v[218:221] offset:40960
	ds_write_b128 v11, v[222:225] offset:49152
	ds_write_b128 v12, v[226:229] offset:57344
	v_cmp_gt_u32_e32 vcc, 0x80, v3
	s_and_saveexec_b64 s[16:17], vcc
	v_add_u32_e32 v10, 0x10000, v11
	ds_write_b128 v10, v[240:243]
	s_or_b64 exec, exec, s[16:17]
